# barriers: invalidate on wave 1 at entry; leftover vmcnt waits behind thread 0 release atomics dropped
# baseline (speedup 1.0000x reference)
.LBB0_78:
	s_or_b64 exec, exec, s[14:15]
	s_xor_b64 s[12:13], s[16:17], -1
	s_and_saveexec_b64 s[14:15], s[12:13]
	s_xor_b64 s[14:15], exec, s[14:15]
	s_cbranch_execz .LBB0_81
	s_mov_b64 s[12:13], exec
	v_mbcnt_lo_u32_b32 v1, s12, 0
	v_mbcnt_hi_u32_b32 v1, s13, v1
	v_cmp_eq_u32_e32 vcc, 0, v1
	s_and_b64 s[14:15], exec, vcc
	s_mov_b64 exec, s[14:15]
	s_cbranch_execz .LBB0_81
	s_bcnt1_i32_b64 s12, s[12:13]
	v_mov_b32_e32 v1, 0
	v_mov_b32_e32 v2, s12
	global_atomic_add v1, v2, s[10:11]
.LBB0_81:
	s_or_b64 exec, exec, s[8:9]
	s_waitcnt lgkmcnt(0)
.LBB0_82:
	s_andn2_saveexec_b64 s[6:7], s[6:7]
	s_cbranch_execz .LBB0_132
	s_mov_b64 s[6:7], exec
	buffer_wbl2 sc1
	s_waitcnt lgkmcnt(0)
	s_waitcnt vmcnt(0)
	v_mbcnt_lo_u32_b32 v2, s6, 0
	v_mbcnt_hi_u32_b32 v2, s7, v2
	v_cmp_eq_u32_e32 vcc, 0, v2
	s_and_saveexec_b64 s[8:9], vcc
	s_cbranch_execz .LBB0_85
	s_bcnt1_i32_b64 s6, s[6:7]
	v_mov_b32_e32 v3, 0x7000
	v_mov_b32_e32 v4, s6
	global_atomic_add v3, v3, v4, s[46:47] offset:1024 sc0

.LBB0_131:
	s_or_b64 exec, exec, s[4:5]
.LBB0_132:
	s_or_b64 exec, exec, s[18:19]
	s_add_i32 s6, 0, 0x24168
	s_mov_b64 s[4:5], s[0:1]
	v_mov_b32_e32 v2, v0
	v_mov_b32_e32 v1, s6
	s_waitcnt lgkmcnt(0)
	s_barrier
	ds_read_b32 v1, v1
	s_add_i32 s6, 0, 0x2416c
	v_mov_b32_e32 v3, s6
	ds_read_b32 v3, v3
	v_readfirstlane_b32 s8, v2
	s_waitcnt lgkmcnt(1)
	v_readfirstlane_b32 s6, v1
	s_cmp_eq_u32 s6, 2
	s_cselect_b64 s[6:7], -1, 0
	s_and_b64 s[6:7], s[24:25], s[6:7]
	s_waitcnt lgkmcnt(0)
	v_readfirstlane_b32 s9, v3
	s_andn2_b64 vcc, exec, s[6:7]
	s_mov_b64 s[6:7], -1
	s_cbranch_vccnz .LBB0_135
	s_cmp_lt_u32 s33, 8
	s_cselect_b64 s[6:7], -1, 0
	s_cmp_lt_u32 s9, 32
	s_cselect_b64 s[10:11], -1, 0
	s_and_b64 s[6:7], s[6:7], s[10:11]
	s_andn2_b64 vcc, exec, s[6:7]
	s_mov_b64 s[6:7], -1
	s_cbranch_vccnz .LBB0_135
	s_lshl_b32 s2, s33, 5
	s_or_b32 s54, s9, s2
	s_lshl_b32 s2, s9, 3
	s_or_b32 s2, s2, s33
	s_mov_b64 s[6:7], 0

.LBB0_156:
	s_or_b64 exec, exec, s[8:9]
.LBB0_157:
	s_or_b64 exec, exec, s[6:7]
	s_mov_b64 s[6:7], 0
	s_barrier

.LBB0_190:
	s_or_b64 exec, exec, s[10:11]
	s_waitcnt lgkmcnt(0)

.LBB0_240:
	s_or_b64 exec, exec, s[6:7]
.LBB0_241:
	s_or_b64 exec, exec, s[20:21]
	s_waitcnt lgkmcnt(0)
	s_barrier

.LBB0_396:
	s_or_b64 exec, exec, s[18:19]
	s_xor_b64 s[16:17], s[20:21], -1
	s_and_saveexec_b64 s[18:19], s[16:17]
	s_xor_b64 s[18:19], exec, s[18:19]
	s_cbranch_execz .LBB0_399
	s_mov_b64 s[16:17], exec
	v_mbcnt_lo_u32_b32 v2, s16, 0
	v_mbcnt_hi_u32_b32 v2, s17, v2
	v_cmp_eq_u32_e32 vcc, 0, v2
	s_and_b64 s[18:19], exec, vcc
	s_mov_b64 exec, s[18:19]
	s_cbranch_execz .LBB0_399
	s_bcnt1_i32_b64 s16, s[16:17]
	v_mov_b32_e32 v2, 0
	v_mov_b32_e32 v3, s16
	global_atomic_add v2, v3, s[14:15]
.LBB0_399:
	s_or_b64 exec, exec, s[12:13]
	s_waitcnt lgkmcnt(0)
.LBB0_400:
	s_andn2_saveexec_b64 s[10:11], s[10:11]
	s_cbranch_execz .LBB0_450
	s_mov_b64 s[10:11], exec
	buffer_wbl2 sc1
	s_waitcnt lgkmcnt(0)
	s_waitcnt vmcnt(0)
	v_mbcnt_lo_u32_b32 v3, s10, 0
	v_mbcnt_hi_u32_b32 v3, s11, v3
	v_cmp_eq_u32_e32 vcc, 0, v3
	s_and_saveexec_b64 s[12:13], vcc
	s_cbranch_execz .LBB0_403
	s_bcnt1_i32_b64 s10, s[10:11]
	v_mov_b32_e32 v4, 0x7000
	v_mov_b32_e32 v5, s10
	global_atomic_add v4, v4, v5, s[46:47] offset:1024 sc0

.LBB0_449:
	s_or_b64 exec, exec, s[6:7]
.LBB0_450:
	s_or_b64 exec, exec, s[22:23]
	s_mov_b64 s[6:7], s[0:1]
	v_mov_b32_e32 v2, v0
	s_waitcnt lgkmcnt(0)
	s_barrier
	s_load_dwordx2 s[30:31], s[6:7], 0x0
	v_mov_b32_e32 v236, v0
	s_cmpk_lt_i32 s2, 0x100
	s_cselect_b64 s[10:11], -1, 0
	s_cmpk_gt_i32 s2, 0xff
	v_readfirstlane_b32 s70, v236
	s_cbranch_scc1 .LBB0_456
	s_ashr_i32 s12, s2, 31
	s_lshr_b32 s12, s12, 29
	s_add_i32 s14, s2, s12
	s_and_b32 s12, s14, -8
	s_sub_i32 s15, s2, s12
	s_cmp_gt_i32 s15, -1
	s_cbranch_scc0 .LBB0_453
	s_lshl_b32 s16, s15, 5
	s_cbranch_execz .LBB0_454
	s_branch .LBB0_455

.LBB0_600:
	s_or_b64 exec, exec, s[12:13]
.LBB0_601:
	s_or_b64 exec, exec, s[10:11]
	s_barrier
	s_branch .LBB0_685

.LBB0_630:
	s_or_b64 exec, exec, s[20:21]
	s_xor_b64 s[18:19], s[22:23], -1
	s_and_saveexec_b64 s[20:21], s[18:19]
	s_xor_b64 s[20:21], exec, s[20:21]
	s_cbranch_execz .LBB0_633
	s_mov_b64 s[18:19], exec
	v_mbcnt_lo_u32_b32 v2, s18, 0
	v_mbcnt_hi_u32_b32 v2, s19, v2
	v_cmp_eq_u32_e32 vcc, 0, v2
	s_and_b64 s[20:21], exec, vcc
	s_mov_b64 exec, s[20:21]
	s_cbranch_execz .LBB0_633
	s_bcnt1_i32_b64 s18, s[18:19]
	v_mov_b32_e32 v2, 0
	v_mov_b32_e32 v3, s18
	global_atomic_add v2, v3, s[16:17]
.LBB0_633:
	s_or_b64 exec, exec, s[14:15]
	s_waitcnt lgkmcnt(0)
.LBB0_634:
	s_andn2_saveexec_b64 s[12:13], s[12:13]
	s_cbranch_execz .LBB0_684
	s_mov_b64 s[12:13], exec
	buffer_wbl2 sc1
	s_waitcnt lgkmcnt(0)
	s_waitcnt vmcnt(0)
	v_mbcnt_lo_u32_b32 v3, s12, 0
	v_mbcnt_hi_u32_b32 v3, s13, v3
	v_cmp_eq_u32_e32 vcc, 0, v3
	s_and_saveexec_b64 s[14:15], vcc
	s_cbranch_execz .LBB0_637
	s_bcnt1_i32_b64 s12, s[12:13]
	v_mov_b32_e32 v4, 0x7000
	v_mov_b32_e32 v5, s12
	global_atomic_add v4, v4, v5, s[46:47] offset:1024 sc0

.LBB0_683:
	s_or_b64 exec, exec, s[10:11]
.LBB0_684:
	s_or_b64 exec, exec, s[28:29]
	s_waitcnt lgkmcnt(0)
	s_barrier

.LBB0_787:
	s_or_b64 exec, exec, s[18:19]
	s_xor_b64 s[16:17], s[20:21], -1
	s_and_saveexec_b64 s[18:19], s[16:17]
	s_xor_b64 s[18:19], exec, s[18:19]
	s_cbranch_execz .LBB0_790
	s_mov_b64 s[16:17], exec
	v_mbcnt_lo_u32_b32 v2, s16, 0
	v_mbcnt_hi_u32_b32 v2, s17, v2
	v_cmp_eq_u32_e32 vcc, 0, v2
	s_and_b64 s[18:19], exec, vcc
	s_mov_b64 exec, s[18:19]
	s_cbranch_execz .LBB0_790
	s_bcnt1_i32_b64 s16, s[16:17]
	v_mov_b32_e32 v2, 0
	v_mov_b32_e32 v3, s16
	global_atomic_add v2, v3, s[14:15]
.LBB0_790:
	s_or_b64 exec, exec, s[12:13]
	s_waitcnt lgkmcnt(0)
.LBB0_791:
	s_andn2_saveexec_b64 s[10:11], s[10:11]
	s_cbranch_execz .LBB0_841
	s_mov_b64 s[10:11], exec
	buffer_wbl2 sc1
	s_waitcnt lgkmcnt(0)
	s_waitcnt vmcnt(0)
	v_mbcnt_lo_u32_b32 v3, s10, 0
	v_mbcnt_hi_u32_b32 v3, s11, v3
	v_cmp_eq_u32_e32 vcc, 0, v3
	s_and_saveexec_b64 s[12:13], vcc
	s_cbranch_execz .LBB0_794
	s_bcnt1_i32_b64 s10, s[10:11]
	v_mov_b32_e32 v4, 0x7000
	v_mov_b32_e32 v5, s10
	global_atomic_add v4, v4, v5, s[46:47] offset:1024 sc0

.LBB0_840:
	s_or_b64 exec, exec, s[8:9]
.LBB0_841:
	s_or_b64 exec, exec, s[22:23]
	s_mov_b64 s[22:23], s[0:1]
	v_mov_b32_e32 v123, v0
	s_waitcnt lgkmcnt(0)
	s_barrier
	s_nop 0
	v_readfirstlane_b32 s56, v123
	s_ashr_i32 s20, s56, 6
	s_add_i32 s40, s20, s55
	s_cmpk_gt_i32 s40, 0x7ff
	v_and_b32_e32 v122, 63, v123
	s_cbranch_scc1 .LBB0_846
	s_load_dwordx2 s[34:35], s[22:23], 0x90
	s_load_dwordx2 s[24:25], s[22:23], 0x38
	s_lshl_b32 s28, s3, 3
	v_mbcnt_hi_u32_b32 v2, -1, v1
	v_and_b32_e32 v3, 64, v2
	s_waitcnt lgkmcnt(0)
	s_add_u32 s41, s34, 0x200000
	s_addc_u32 s42, s35, 0
	s_add_u32 s43, s34, 0x300000
	s_addc_u32 s50, s35, 0
	s_ashr_i32 s21, s20, 31
	s_ashr_i32 s29, s55, 31
	s_add_u32 s36, s20, s55
	s_addc_u32 s37, s21, s29
	s_lshl_b64 s[36:37], s[36:37], 2
	s_add_u32 s21, s34, s36
	v_add_u32_e32 v4, -1, v2
	v_add_u32_e32 v5, -2, v2
	v_add_u32_e32 v6, -4, v2
	v_add_u32_e32 v7, -8, v2
	v_add_u32_e32 v8, -16, v2
	v_subrev_u32_e32 v9, 32, v2
	s_addc_u32 s29, s35, s37
	v_cmp_lt_i32_e32 vcc, v4, v3
	v_cmp_lt_i32_e64 s[8:9], v5, v3
	v_cmp_lt_i32_e64 s[10:11], v6, v3
	v_cmp_lt_i32_e64 s[12:13], v7, v3
	v_cmp_lt_i32_e64 s[14:15], v8, v3
	v_cmp_lt_i32_e64 s[16:17], v9, v3
	s_add_u32 s34, s21, 0x3c0000
	v_cndmask_b32_e32 v4, v4, v2, vcc
	v_cndmask_b32_e64 v5, v5, v2, s[8:9]
	v_cndmask_b32_e64 v6, v6, v2, s[10:11]
	v_cndmask_b32_e64 v7, v7, v2, s[12:13]
	v_cndmask_b32_e64 v8, v8, v2, s[14:15]
	v_cndmask_b32_e64 v2, v9, v2, s[16:17]
	s_addc_u32 s35, s29, 0
	s_ashr_i32 s29, s28, 31
	s_lshl_b32 s21, s54, 9
	s_lshl_b32 s20, s20, 6
	s_mov_b32 s31, 0
	v_lshlrev_b32_e32 v4, 2, v4
	v_cmp_eq_u32_e32 vcc, 0, v122
	v_lshlrev_b32_e32 v5, 2, v5
	v_cmp_gt_u32_e64 s[8:9], 2, v122
	v_lshlrev_b32_e32 v6, 2, v6
	v_cmp_gt_u32_e64 s[10:11], 4, v122
	v_lshlrev_b32_e32 v7, 2, v7
	v_cmp_gt_u32_e64 s[12:13], 8, v122
	v_lshlrev_b32_e32 v8, 2, v8
	v_cmp_gt_u32_e64 s[14:15], 16, v122
	v_lshlrev_b32_e32 v9, 2, v2
	v_cmp_gt_u32_e64 s[16:17], 32, v122
	v_cmp_eq_u32_e64 s[18:19], 63, v122
	s_lshl_b64 s[36:37], s[28:29], 2
	s_add_i32 s29, s21, s20
	s_lshl_b32 s51, s3, 9
	v_mov_b32_e32 v3, 0
	s_mov_b32 s55, 0xbfb8aa3b
	s_mov_b32 s57, 0x3f2aaaab
	v_mov_b32_e32 v10, 0x3ecc95a3
	s_mov_b32 s58, 0x3f317218
	s_mov_b32 s59, 0x7f800000
	v_mov_b32_e32 v11, 0x7f800000
	v_mov_b32_e32 v12, 0x7fc00000
	v_mov_b32_e32 v13, 0xff800000
	s_mov_b32 s60, 0x33800000
	s_branch .LBB0_844

.LBB0_910:
	s_or_b64 exec, exec, s[18:19]
	s_xor_b64 s[16:17], s[20:21], -1
	s_and_saveexec_b64 s[18:19], s[16:17]
	s_xor_b64 s[18:19], exec, s[18:19]
	s_cbranch_execz .LBB0_913
	s_mov_b64 s[16:17], exec
	v_mbcnt_lo_u32_b32 v2, s16, 0
	v_mbcnt_hi_u32_b32 v2, s17, v2
	v_cmp_eq_u32_e32 vcc, 0, v2
	s_and_b64 s[18:19], exec, vcc
	s_mov_b64 exec, s[18:19]
	s_cbranch_execz .LBB0_913
	s_bcnt1_i32_b64 s16, s[16:17]
	v_mov_b32_e32 v2, 0
	v_mov_b32_e32 v3, s16
	global_atomic_add v2, v3, s[14:15]
.LBB0_913:
	s_or_b64 exec, exec, s[12:13]
	s_waitcnt lgkmcnt(0)
.LBB0_914:
	s_andn2_saveexec_b64 s[10:11], s[10:11]
	s_cbranch_execz .LBB0_964
	s_mov_b64 s[10:11], exec
	buffer_wbl2 sc1
	s_waitcnt lgkmcnt(0)
	s_waitcnt vmcnt(0)
	v_mbcnt_lo_u32_b32 v3, s10, 0
	v_mbcnt_hi_u32_b32 v3, s11, v3
	v_cmp_eq_u32_e32 vcc, 0, v3
	s_and_saveexec_b64 s[12:13], vcc
	s_cbranch_execz .LBB0_917
	s_bcnt1_i32_b64 s10, s[10:11]
	v_mov_b32_e32 v4, 0x7000
	v_mov_b32_e32 v5, s10
	global_atomic_add v4, v4, v5, s[46:47] offset:1024 sc0

.LBB0_963:
	s_or_b64 exec, exec, s[8:9]
.LBB0_964:
	s_or_b64 exec, exec, s[22:23]
	s_mov_b64 s[26:27], s[0:1]
	v_mov_b32_e32 v132, v0
	s_waitcnt lgkmcnt(0)
	s_barrier
	s_mov_b64 s[8:9], -1
	v_readfirstlane_b32 s40, v132
	s_and_b64 vcc, exec, s[52:53]
	s_cbranch_vccz .LBB0_1075
	s_cmp_gt_i32 s2, 63
	s_cbranch_scc1 .LBB0_1074
	v_mov_b32_e32 v103, 0
	s_movk_i32 s41, 0x80
	s_mov_b64 s[16:17], 0xd000000
	s_movk_i32 s42, 0xff
	s_movk_i32 s43, 0x100
	s_mov_b64 s[18:19], 0xe000000
	v_mov_b32_e32 v133, 0xf210000
	s_movk_i32 s50, 0x90
	s_add_i32 s51, 0, 0x9400
	s_mov_b64 s[20:21], 0x40800
	s_mov_b64 s[22:23], 0x20000
	v_mov_b32_e32 v138, v103
	v_mov_b32_e32 v139, v103
	v_mov_b32_e32 v134, 0x3f803f80
	v_mov_b32_e32 v135, 0x204000
	s_mov_b32 s55, s2
	s_mov_b32 s56, s2
	s_branch .LBB0_968

.LBB0_1311:
	s_or_b64 exec, exec, s[18:19]
	s_xor_b64 s[16:17], s[20:21], -1
	s_and_saveexec_b64 s[18:19], s[16:17]
	s_xor_b64 s[18:19], exec, s[18:19]
	s_cbranch_execz .LBB0_1314
	s_mov_b64 s[16:17], exec
	v_mbcnt_lo_u32_b32 v2, s16, 0
	v_mbcnt_hi_u32_b32 v2, s17, v2
	v_cmp_eq_u32_e32 vcc, 0, v2
	s_and_b64 s[18:19], exec, vcc
	s_mov_b64 exec, s[18:19]
	s_cbranch_execz .LBB0_1314
	s_bcnt1_i32_b64 s16, s[16:17]
	v_mov_b32_e32 v2, 0
	v_mov_b32_e32 v3, s16
	global_atomic_add v2, v3, s[14:15]
.LBB0_1314:
	s_or_b64 exec, exec, s[12:13]
	s_waitcnt lgkmcnt(0)
.LBB0_1315:
	s_andn2_saveexec_b64 s[10:11], s[10:11]
	s_cbranch_execz .LBB0_1365
	s_mov_b64 s[10:11], exec
	buffer_wbl2 sc1
	s_waitcnt lgkmcnt(0)
	s_waitcnt vmcnt(0)
	v_mbcnt_lo_u32_b32 v3, s10, 0
	v_mbcnt_hi_u32_b32 v3, s11, v3
	v_cmp_eq_u32_e32 vcc, 0, v3
	s_and_saveexec_b64 s[12:13], vcc
	s_cbranch_execz .LBB0_1318
	s_bcnt1_i32_b64 s10, s[10:11]
	v_mov_b32_e32 v4, 0x7000
	v_mov_b32_e32 v5, s10
	global_atomic_add v4, v4, v5, s[46:47] offset:1024 sc0

.LBB0_1364:
	s_or_b64 exec, exec, s[8:9]
.LBB0_1365:
	s_or_b64 exec, exec, s[22:23]
	s_mov_b64 s[58:59], s[0:1]
	v_mov_b32_e32 v172, v0
	s_waitcnt lgkmcnt(0)
	s_barrier
	s_mov_b64 s[8:9], -1
	v_readfirstlane_b32 s71, v172
	v_and_b32_e32 v171, 63, v172
	s_ashr_i32 s70, s71, 6
	s_and_b64 vcc, exec, s[4:5]
	v_lshlrev_b32_e32 v196, 3, v172
	v_ashrrev_i32_e32 v166, 4, v172
	s_cbranch_vccnz .LBB0_1550
	s_ashr_i32 s25, s54, 4
	s_load_dwordx2 s[34:35], s[58:59], 0x90
	s_and_b32 s8, s25, -4
	s_bfe_u32 s24, s54, 0x20003
	s_or_b32 s60, s8, s24
	s_lshl_b32 s8, s54, 2
	s_and_b32 s8, s8, 28
	s_and_b32 s9, s54, 32
	s_ashr_i32 s20, s54, 6
	s_or_b32 s22, s8, s9
	s_ashr_i32 s21, s20, 31
	s_waitcnt lgkmcnt(0)
	s_add_u32 s76, s34, 0x3000000
	s_addc_u32 s77, s35, 0
	s_lshl_b64 s[8:9], s[20:21], 22
	s_add_u32 s8, s76, s8
	s_addc_u32 s9, s77, s9
	s_lshl_b32 s10, s22, 16
	s_add_u32 s8, s8, s10
	s_addc_u32 s9, s9, 0
	s_lshl_b32 s10, s24, 8
	s_add_u32 s8, s8, s10
	s_addc_u32 s9, s9, 0
	s_add_u32 s74, s34, 0xd000000
	s_addc_u32 s75, s35, 0
	s_ashr_i32 s61, s60, 31
	s_lshl_b64 s[10:11], s[60:61], 6
	s_or_b32 s10, s10, s22
	s_lshl_b64 s[12:13], s[10:11], 14
	s_add_u32 s14, s74, s12
	s_addc_u32 s15, s75, s13
	s_add_u32 s78, s34, 0xe000000
	s_addc_u32 s79, s35, 0
	v_and_b32_e32 v2, 0x78, v196
	s_add_u32 s12, s78, s12
	s_waitcnt vmcnt(2)
	v_mov_b32_e32 v62, 0
	v_lshlrev_b32_e32 v180, 1, v2
	v_and_b32_e32 v2, 56, v196
	v_and_b32_e32 v6, 0xffffffc0, v196
	s_addc_u32 s13, s79, s13
	v_mov_b32_e32 v181, v62
	v_lshlrev_b32_e32 v182, 1, v2
	v_mov_b32_e32 v183, v62
	v_ashrrev_i32_e32 v167, 31, v166
	v_ashrrev_i32_e32 v7, 31, v6
	v_lshl_add_u64 v[4:5], s[8:9], 0, v[180:181]
	v_lshl_add_u64 v[8:9], s[12:13], 0, v[182:183]
	v_lshlrev_b64 v[184:185], 10, v[166:167]
	v_lshlrev_b64 v[186:187], 1, v[6:7]
	v_lshl_add_u64 v[2:3], v[4:5], 0, v[184:185]
	v_lshl_add_u64 v[6:7], v[8:9], 0, v[186:187]
	global_load_dwordx4 v[46:49], v[2:3], off nt
	global_load_dwordx4 v[50:53], v[6:7], off nt
	v_add_u32_e32 v6, 0x200, v172
	v_ashrrev_i32_e32 v2, 4, v6
	v_ashrrev_i32_e32 v3, 31, v2
	v_lshl_add_u64 v[10:11], s[14:15], 0, v[182:183]
	v_lshlrev_b64 v[188:189], 10, v[2:3]
	v_lshl_add_u64 v[12:13], v[10:11], 0, v[186:187]
	v_lshl_add_u64 v[4:5], v[4:5], 0, v[188:189]
	v_lshlrev_b32_e32 v223, 3, v6
	global_load_dwordx4 v[54:57], v[12:13], off nt
	global_load_dwordx4 v[58:61], v[4:5], off nt
	v_and_b32_e32 v4, 0xffffffc0, v223
	v_ashrrev_i32_e32 v5, 31, v4
	v_lshlrev_b64 v[190:191], 1, v[4:5]
	v_lshl_add_u64 v[4:5], v[8:9], 0, v[190:191]
	v_lshl_add_u64 v[8:9], v[10:11], 0, v[190:191]
	global_load_dwordx4 v[66:69], v[4:5], off nt
	global_load_dwordx4 v[70:73], v[8:9], off nt
	s_mul_i32 s8, s10, 0x8100
	s_mul_hi_u32 s9, s10, 0x8100
	s_mul_i32 s10, s11, 0x8100
	s_add_i32 s9, s9, s10
	s_add_u32 s80, s34, 0x9000000
	s_addc_u32 s81, s35, 0
	s_add_u32 s8, s80, s8
	s_addc_u32 s9, s81, s9
	v_lshl_add_u64 v[4:5], s[8:9], 0, v[180:181]
	s_movk_i32 s8, 0x810
	v_cmp_gt_i32_e64 s[8:9], s8, v172
	s_waitcnt vmcnt(7)
	v_mov_b32_e32 v74, 0
	v_mov_b32_e32 v75, v62
	v_mov_b32_e32 v76, v62
	v_mov_b32_e32 v77, v62
	s_and_saveexec_b64 s[10:11], s[8:9]
	s_cbranch_execz .LBB0_1368
	v_and_b32_e32 v8, 0xffffff80, v196
	v_ashrrev_i32_e32 v9, 31, v8
	v_lshl_add_u64 v[8:9], v[8:9], 1, v[4:5]
	global_load_dwordx4 v[74:77], v[8:9], off nt

.LBB0_1669:
	s_or_b64 exec, exec, s[10:11]
.LBB0_1670:
	s_or_b64 exec, exec, s[8:9]
	s_mov_b64 s[8:9], 0
	s_barrier

.LBB0_1700:
	s_or_b64 exec, exec, s[18:19]
	s_xor_b64 s[16:17], s[20:21], -1
	s_and_saveexec_b64 s[18:19], s[16:17]
	s_xor_b64 s[18:19], exec, s[18:19]
	s_cbranch_execz .LBB0_1703
	s_mov_b64 s[16:17], exec
	v_mbcnt_lo_u32_b32 v2, s16, 0
	v_mbcnt_hi_u32_b32 v2, s17, v2
	v_cmp_eq_u32_e32 vcc, 0, v2
	s_and_b64 s[18:19], exec, vcc
	s_mov_b64 exec, s[18:19]
	s_cbranch_execz .LBB0_1703
	s_bcnt1_i32_b64 s16, s[16:17]
	v_mov_b32_e32 v2, 0
	v_mov_b32_e32 v3, s16
	global_atomic_add v2, v3, s[14:15]
.LBB0_1703:
	s_or_b64 exec, exec, s[12:13]
	s_waitcnt lgkmcnt(0)
.LBB0_1704:
	s_andn2_saveexec_b64 s[10:11], s[10:11]
	s_cbranch_execz .LBB0_1754
	s_mov_b64 s[10:11], exec
	buffer_wbl2 sc1
	s_waitcnt lgkmcnt(0)
	s_waitcnt vmcnt(0)
	v_mbcnt_lo_u32_b32 v3, s10, 0
	v_mbcnt_hi_u32_b32 v3, s11, v3
	v_cmp_eq_u32_e32 vcc, 0, v3
	s_and_saveexec_b64 s[12:13], vcc
	s_cbranch_execz .LBB0_1707
	s_bcnt1_i32_b64 s10, s[10:11]
	v_mov_b32_e32 v4, 0x7000
	v_mov_b32_e32 v5, s10
	global_atomic_add v4, v4, v5, s[46:47] offset:1024 sc0

.LBB0_1753:
	s_or_b64 exec, exec, s[8:9]
.LBB0_1754:
	s_or_b64 exec, exec, s[22:23]
	s_waitcnt lgkmcnt(0)
	s_barrier

.LBB0_1880:
	s_or_b64 exec, exec, s[10:11]
.LBB0_1881:
	s_or_b64 exec, exec, s[8:9]
	s_barrier
	s_branch .LBB0_1965

.LBB0_1910:
	s_or_b64 exec, exec, s[18:19]
	s_xor_b64 s[16:17], s[20:21], -1
	s_and_saveexec_b64 s[18:19], s[16:17]
	s_xor_b64 s[18:19], exec, s[18:19]
	s_cbranch_execz .LBB0_1913
	s_mov_b64 s[16:17], exec
	v_mbcnt_lo_u32_b32 v2, s16, 0
	v_mbcnt_hi_u32_b32 v2, s17, v2
	v_cmp_eq_u32_e32 vcc, 0, v2
	s_and_b64 s[18:19], exec, vcc
	s_mov_b64 exec, s[18:19]
	s_cbranch_execz .LBB0_1913
	s_bcnt1_i32_b64 s16, s[16:17]
	v_mov_b32_e32 v2, 0
	v_mov_b32_e32 v3, s16
	global_atomic_add v2, v3, s[14:15]
.LBB0_1913:
	s_or_b64 exec, exec, s[12:13]
	s_waitcnt lgkmcnt(0)
.LBB0_1914:
	s_andn2_saveexec_b64 s[10:11], s[10:11]
	s_cbranch_execz .LBB0_1964
	s_mov_b64 s[10:11], exec
	buffer_wbl2 sc1
	s_waitcnt lgkmcnt(0)
	s_waitcnt vmcnt(0)
	v_mbcnt_lo_u32_b32 v3, s10, 0
	v_mbcnt_hi_u32_b32 v3, s11, v3
	v_cmp_eq_u32_e32 vcc, 0, v3
	s_and_saveexec_b64 s[12:13], vcc
	s_cbranch_execz .LBB0_1917
	s_bcnt1_i32_b64 s10, s[10:11]
	v_mov_b32_e32 v4, 0x7000
	v_mov_b32_e32 v5, s10
	global_atomic_add v4, v4, v5, s[46:47] offset:1024 sc0

.LBB0_1963:
	s_or_b64 exec, exec, s[8:9]
.LBB0_1964:
	s_or_b64 exec, exec, s[22:23]
	s_waitcnt lgkmcnt(0)
	s_barrier

.LBB0_2025:
	s_or_b64 exec, exec, s[8:9]
.LBB0_2026:
	s_or_b64 exec, exec, s[4:5]
	s_barrier
	s_branch .LBB0_2110

.LBB0_2108:
	s_or_b64 exec, exec, s[4:5]
.LBB0_2109:
	s_or_b64 exec, exec, s[20:21]
	s_waitcnt lgkmcnt(0)
	s_barrier
